# ballot trim: differential mixer early-exit test compares the v_cmp lane mask with exec directly (3 instructions fewer per key-tile step)
# baseline (speedup 1.0000x reference)
; template <int VAR>
; __device__ __forceinline__ void attn_unit(LAS unsigned char* lds, const AttnArgs& A, int b, int h, int qb, const int tid) {
;     ...
;                 { const float bf = -slope2 * (float)(tl + 4 * hi + 1);
;                   wdone = __all((qkb1 + bf - m1 < -151.0f) && (qkb2 + bf - m2 < -151.0f)); }
.LBB0_469:
	v_add_u32_e32 v66, 0xffffff41, v141
	v_cvt_f32_i32_e32 v66, v66
	v_mul_f32_e32 v66, v138, v66
	v_pk_add_f32 v[66:67], v[132:133], v[66:67] op_sel_hi:[1,0]
	s_nop 0
	v_pk_add_f32 v[66:67], v[66:67], v[134:135] neg_lo:[0,1] neg_hi:[0,1]
	s_nop 0
	v_cmp_gt_f32_e32 vcc, s36, v66
	v_cmp_gt_f32_e64 s[12:13], s36, v67
	s_and_b64 s[12:13], s[12:13], vcc
	s_cmp_eq_u64 s[12:13], exec
	s_cselect_b64 s[12:13], -1, 0
	s_add_i32 s50, s70, 1
	s_cmp_ge_u32 s50, s82
	s_cbranch_scc1 .LBB0_471
